# v27: v26 + static re-assignment: M3 classes (2P+G | P+2S+G | P+S+2G | P+4G), M1 fourth-round items moved to workgroups 16..31
# baseline (speedup 1.0000x reference)
; DI KA get_ka() { KA p = (KA)__builtin_amdgcn_kernarg_segment_ptr(); asm volatile("" : "+s"(p)); return p; }
; __global__ void __launch_bounds__(512, 2) hymba_fwd(Args a_unused) {
;     ...
;         for (int rep = 0; rep < REP_M1; ++rep)
;         for (int it = blockIdx.x; it < 2 * NUNIT; it += gridDim.x) gla_unit<false>(get_ka(), l, it, lds);
.LBB0_602:
	s_waitcnt lgkmcnt(0)
	s_barrier
	v_readlane_b32 s2, v254, 12
	s_add_i32 s33, s33, s2
	v_readlane_b32 s3, v254, 13
	s_cmpk_lt_i32 s33, 0x300
	s_cbranch_scc1 .LBB0_603
	s_cmpk_gt_i32 s33, 0x3ff
	s_cbranch_scc1 .LBB0_599
	s_add_i32 s4, s33, 0xfffffcf0
	s_cmp_lt_u32 s4, 16
	s_cbranch_scc0 .LBB0_599
	s_add_i32 s33, s4, 0x300

; #define LBAR() do { asm volatile("s_waitcnt lgkmcnt(0)" ::: "memory"); __builtin_amdgcn_s_barrier(); asm volatile("" ::: "memory"); } while (0)
; DI KA get_ka() { KA p = (KA)__builtin_amdgcn_kernarg_segment_ptr(); asm volatile("" : "+s"(p)); return p; }
; __global__ void __launch_bounds__(512, 2) hymba_fwd(Args a_unused) {
;     ...
;         for (int it = blockIdx.x; it < NUNIT + 2 * NUNIT; it += gridDim.x) {
;             if (it < NUNIT) { lru_unit<true>(get_ka(), l, it, lds); LBAR(); }
;             else { for (int rep = 0; rep < REP_M3G; ++rep) gla_unit<true>(get_ka(), l, it - NUNIT, lds); }
;         }
.LBB0_791:
	v_readlane_b32 s2, v254, 0
	s_cmpk_lt_i32 s62, 0x188
	s_cbranch_scc0 .Lm3_adv_gla
	s_cmp_eq_u32 s62, s2
	s_cbranch_scc0 .Lm3_lru2
	s_cmpk_lt_i32 s2, 8
	s_cbranch_scc0 .Lm3_n1
	s_add_i32 s62, s2, 0x100
	s_branch .LBB0_792
.Lm3_n1:
	s_cmpk_lt_i32 s2, 48
	s_cbranch_scc0 .Lm3_n2
	s_lshl_b32 s62, s2, 1
	s_addk_i32 s62, 0xf8
	s_branch .LBB0_792
.Lm3_n2:
	s_cmpk_lt_i32 s2, 0x60
	s_cbranch_scc0 .Lm3_n3
	s_add_i32 s62, s2, 0x128
	s_branch .LBB0_792
.Lm3_n3:
	s_lshl_b32 s62, s2, 2
	s_addk_i32 s62, 0x98
	s_branch .LBB0_792
.Lm3_lru2:
	s_cmpk_lt_i32 s2, 8
	s_cbranch_scc1 .Lm3_g_ab
	s_cmpk_lt_i32 s2, 48
	s_cbranch_scc0 .Lm3_l2c
	s_lshl_b32 s3, s2, 1
	s_addk_i32 s3, 0xf8
	s_cmp_eq_u32 s62, s3
	s_cbranch_scc0 .Lm3_g_ab
	s_add_i32 s62, s62, 1
	s_branch .LBB0_792
.Lm3_g_ab:
	s_add_i32 s62, s2, 0x188
	s_branch .LBB0_792
.Lm3_l2c:
	s_lshl_b32 s62, s2, 1
	s_addk_i32 s62, 0x158
	s_branch .LBB0_792
.Lm3_adv_gla:
	s_cmpk_lt_i32 s2, 48
	s_cbranch_scc1 .LBB0_1057
	s_cmpk_lt_i32 s2, 0x60
	s_cbranch_scc0 .Lm3_adv_d
	s_lshl_b32 s3, s2, 1
	s_addk_i32 s3, 0x158
	s_cmp_eq_u32 s62, s3
	s_cbranch_scc0 .LBB0_1057
	s_add_i32 s62, s62, 1
	s_branch .LBB0_792
.Lm3_adv_d:
	s_lshl_b32 s3, s2, 2
	s_addk_i32 s3, 0x9b
	s_cmp_lt_u32 s62, s3
	s_cbranch_scc0 .LBB0_1057
	s_add_i32 s62, s62, 1
	s_branch .LBB0_792
